# SwiGLU and gate-GEMM epilogues: -log2(e) scalings and 1+e adds of adjacent register pairs issued as packed f32 ops (same arithmetic per element); prep_weights round-robin starts at wave 256
# speedup vs baseline: 1.0005x; 1.0005x over previous
; __device__ __forceinline__ unsigned cvt_pk(float lo, float hi) { f32x2_t v = {lo, hi}; bf16x2_t b = __builtin_convertvector(v, bf16x2_t); return __builtin_bit_cast(unsigned, b); }
; __device__ __forceinline__ float ex2(float x) { return __builtin_amdgcn_exp2f(x); }
; __device__ __forceinline__ float sigmoidf_(float x) { return __builtin_amdgcn_rcpf(1.0f + ex2(-x * LOG2E)); }
;     __device__ __forceinline__ void operator()(const f32x4 (&acc)[2][2][4][2], const Unit& u, int wr, int wc, int fr, int fq) const {
;         const int row0 = u.pm * 256 + wr * 64 + fr, col0 = u.pn * 256 + wc * 32 + 8 * fq;
; #pragma unroll
;         for (int bj = 0; bj < 2; ++bj) {
;             const int c = col0 + bj * 128;
;             const f32x4 b0 = *(const f32x4*)(bias + c), b1 = *(const f32x4*)(bias + c + 4);
; #pragma unroll
;             for (int ai = 0; ai < 2; ++ai)
; #pragma unroll
;                 for (int m = 0; m < 4; ++m) {
;                     const f32x4 v0 = acc[ai][bj][m][0] + b0, v1 = acc[ai][bj][m][1] + b1;
;                     u32x4 w; w.x = cvt_pk(sigmoidf_(v0[0]), sigmoidf_(v0[1])); w.y = cvt_pk(sigmoidf_(v0[2]), sigmoidf_(v0[3]));
;                     w.z = cvt_pk(sigmoidf_(v1[0]), sigmoidf_(v1[1])); w.w = cvt_pk(sigmoidf_(v1[2]), sigmoidf_(v1[3]));
;                     *(u32x4*)(G + (size_t)(row0 + ai * 128 + m * 16) * (3 * DM) + c) = w;
;                 }
;         }
;     }
.LBB0_132:
	s_mov_b32 s98, 0xbfb8aa3b
	s_mov_b32 s99, 0xbfb8aa3b
	s_mov_b32 s100, 1.0
	s_mov_b32 s101, 1.0
	v_lshl_or_b32 v160, s13, 8, v153
	v_readlane_b32 s6, v255, 44
	v_ashrrev_i32_e32 v161, 31, v160
	v_readlane_b32 s7, v255, 45
	v_lshl_add_u32 v154, s46, 8, v150
	s_movk_i32 s13, 0x1800
	v_lshl_add_u64 v[148:149], v[160:161], 2, s[6:7]
	global_load_dwordx4 v[106:109], v[148:149], off offset:16
	global_load_dwordx4 v[110:113], v[148:149], off
	v_readlane_b32 s6, v252, 37
	v_readlane_b32 s7, v252, 38
	s_andn2_b64 vcc, exec, s[38:39]
	s_waitcnt vmcnt(0)
	v_pk_add_f32 v[130:131], v[130:131], v[106:107]
	v_pk_add_f32 v[134:135], v[134:135], v[110:111]
	v_pk_add_f32 v[136:137], v[136:137], v[112:113]
	v_pk_mul_f32 v[134:135], v[134:135], s[98:99]
	v_exp_f32_e32 v134, v134
	v_exp_f32_e32 v135, v135
	v_pk_add_f32 v[126:127], v[126:127], v[110:111]
	v_pk_add_f32 v[128:129], v[128:129], v[112:113]
	v_pk_add_f32 v[134:135], v[134:135], s[100:101]
	v_rcp_f32_e32 v134, v134
	v_rcp_f32_e32 v135, v135
	v_pk_mul_f32 v[130:131], v[130:131], s[98:99]
	v_exp_f32_e32 v130, v130
	v_cvt_pk_bf16_f32 v156, v134, v135
	v_pk_mul_f32 v[134:135], v[136:137], s[98:99]
	v_pk_add_f32 v[136:137], v[124:125], v[108:109]
	v_pk_add_f32 v[124:125], v[122:123], v[106:107]
	v_pk_mul_f32 v[122:123], v[126:127], s[98:99]
	v_exp_f32_e32 v122, v122
	v_exp_f32_e32 v123, v123
	v_mul_f32_e32 v126, 0xbfb8aa3b, v129
	v_pk_mul_f32 v[124:125], v[124:125], s[98:99]
	v_pk_add_f32 v[122:123], v[122:123], s[100:101]
	v_rcp_f32_e32 v122, v122
	v_rcp_f32_e32 v123, v123
	v_exp_f32_e32 v126, v126
	v_exp_f32_e32 v124, v124
	v_cvt_pk_bf16_f32 v122, v122, v123
	v_mul_f32_e32 v123, 0xbfb8aa3b, v128
	v_exp_f32_e32 v123, v123
	v_exp_f32_e32 v125, v125
	v_add_f32_e32 v126, 1.0, v126
	v_pk_add_f32 v[124:125], v[124:125], s[100:101]
	v_add_f32_e32 v123, 1.0, v123
	v_rcp_f32_e32 v123, v123
	v_rcp_f32_e32 v126, v126
	v_rcp_f32_e32 v124, v124
	v_rcp_f32_e32 v125, v125
	v_exp_f32_e32 v131, v131
	v_cvt_pk_bf16_f32 v123, v123, v126
	v_mul_f32_e32 v126, 0xbfb8aa3b, v137
	v_cvt_pk_bf16_f32 v124, v124, v125
	v_mul_f32_e32 v125, 0xbfb8aa3b, v136
	v_exp_f32_e32 v125, v125
	v_exp_f32_e32 v126, v126
	v_exp_f32_e32 v134, v134
	v_exp_f32_e32 v135, v135
	v_pk_add_f32 v[130:131], v[130:131], s[100:101]
	v_add_f32_e32 v125, 1.0, v125
	v_add_f32_e32 v126, 1.0, v126
	v_pk_add_f32 v[134:135], v[134:135], s[100:101]
	v_rcp_f32_e32 v130, v130
	v_rcp_f32_e32 v131, v131
	v_rcp_f32_e32 v125, v125
	v_rcp_f32_e32 v126, v126
	v_rcp_f32_e32 v134, v134
	v_rcp_f32_e32 v135, v135
	v_pk_add_f32 v[132:133], v[132:133], v[108:109]
	v_cvt_pk_bf16_f32 v158, v130, v131
	v_pk_mul_f32 v[130:131], v[132:133], s[98:99]
	v_mov_b64_e32 v[132:133], s[6:7]
	v_cvt_pk_bf16_f32 v125, v125, v126
	v_or_b32_e32 v126, 16, v154
	v_cvt_pk_bf16_f32 v157, v134, v135
	v_lshlrev_b64 v[134:135], 1, v[160:161]
	v_mad_i64_i32 v[126:127], s[6:7], v126, s13, v[132:133]
	v_lshl_add_u64 v[126:127], v[126:127], 0, v[134:135]
	v_pk_add_f32 v[118:119], v[118:119], v[110:111]
	global_store_dwordx4 v[126:127], v[122:125], off
	v_pk_add_f32 v[120:121], v[120:121], v[112:113]
	v_pk_add_f32 v[114:115], v[114:115], v[106:107]
	v_pk_add_f32 v[122:123], v[116:117], v[108:109]
	v_pk_mul_f32 v[116:117], v[118:119], s[98:99]
	v_exp_f32_e32 v116, v116
	v_exp_f32_e32 v117, v117
	v_mul_f32_e32 v118, 0xbfb8aa3b, v121
	v_pk_mul_f32 v[114:115], v[114:115], s[98:99]
	v_pk_add_f32 v[116:117], v[116:117], s[100:101]
	v_rcp_f32_e32 v116, v116
	v_rcp_f32_e32 v117, v117
	v_exp_f32_e32 v118, v118
	v_exp_f32_e32 v114, v114
	v_cvt_pk_bf16_f32 v116, v116, v117
	v_mul_f32_e32 v117, 0xbfb8aa3b, v120
	v_exp_f32_e32 v117, v117
	v_exp_f32_e32 v115, v115
	v_add_f32_e32 v118, 1.0, v118
	v_pk_add_f32 v[114:115], v[114:115], s[100:101]
	v_add_f32_e32 v117, 1.0, v117
	v_rcp_f32_e32 v117, v117
	v_rcp_f32_e32 v118, v118
	v_rcp_f32_e32 v114, v114
	v_rcp_f32_e32 v115, v115
	v_pk_add_f32 v[102:103], v[102:103], v[110:111]
	v_cvt_pk_bf16_f32 v117, v117, v118
	v_pk_add_f32 v[104:105], v[104:105], v[112:113]
	v_cvt_pk_bf16_f32 v118, v114, v115
	v_pk_mul_f32 v[114:115], v[122:123], s[98:99]
	v_exp_f32_e32 v114, v114
	v_exp_f32_e32 v115, v115
	v_pk_add_f32 v[98:99], v[98:99], v[106:107]
	v_pk_add_f32 v[94:95], v[94:95], v[110:111]
	v_pk_add_f32 v[114:115], v[114:115], s[100:101]
	v_rcp_f32_e32 v114, v114
	v_rcp_f32_e32 v115, v115
	v_pk_mul_f32 v[98:99], v[98:99], s[98:99]
	v_exp_f32_e32 v98, v98
	v_cvt_pk_bf16_f32 v119, v114, v115
	v_or_b32_e32 v114, 32, v154
	v_mad_i64_i32 v[114:115], s[6:7], v114, s13, v[132:133]
	v_lshl_add_u64 v[114:115], v[114:115], 0, v[134:135]
	global_store_dwordx4 v[114:115], v[116:119], off
	v_exp_f32_e32 v99, v99
	v_add_f32_e32 v98, 1.0, v98
	v_pk_add_f32 v[116:117], v[100:101], v[108:109]
	v_pk_mul_f32 v[100:101], v[102:103], s[98:99]
	v_exp_f32_e32 v100, v100
	v_exp_f32_e32 v101, v101
	v_mul_f32_e32 v102, 0xbfb8aa3b, v105
	v_exp_f32_e32 v102, v102
	v_pk_add_f32 v[100:101], v[100:101], s[100:101]
	v_rcp_f32_e32 v100, v100
	v_rcp_f32_e32 v101, v101
	v_add_f32_e32 v102, 1.0, v102
	v_add_f32_e32 v99, 1.0, v99
	v_rcp_f32_e32 v102, v102
	v_cvt_pk_bf16_f32 v100, v100, v101
	v_mul_f32_e32 v101, 0xbfb8aa3b, v104
	v_exp_f32_e32 v101, v101
	v_rcp_f32_e32 v98, v98
	v_rcp_f32_e32 v99, v99
	v_pk_add_f32 v[96:97], v[96:97], v[112:113]
	v_add_f32_e32 v101, 1.0, v101
	v_rcp_f32_e32 v101, v101
	v_pk_add_f32 v[90:91], v[90:91], v[106:107]
	v_pk_add_f32 v[86:87], v[86:87], v[110:111]
	v_pk_mul_f32 v[90:91], v[90:91], s[98:99]
	v_cvt_pk_bf16_f32 v101, v101, v102
	v_cvt_pk_bf16_f32 v102, v98, v99
	v_pk_mul_f32 v[98:99], v[116:117], s[98:99]
	v_exp_f32_e32 v98, v98
	v_exp_f32_e32 v99, v99
	v_exp_f32_e32 v90, v90
; __device__ __forceinline__ unsigned cvt_pk(float lo, float hi) { f32x2_t v = {lo, hi}; bf16x2_t b = __builtin_convertvector(v, bf16x2_t); return __builtin_bit_cast(unsigned, b); }
; __device__ __forceinline__ float sigmoidf_(float x) { return __builtin_amdgcn_rcpf(1.0f + ex2(-x * LOG2E)); }
;     __device__ __forceinline__ void operator()(const f32x4 (&acc)[2][2][4][2], const Unit& u, int wr, int wc, int fr, int fq) const {
;         const int row0 = u.pm * 256 + wr * 64 + fr, col0 = u.pn * 256 + wc * 32 + 8 * fq;
; #pragma unroll
;         for (int bj = 0; bj < 2; ++bj) {
;             const int c = col0 + bj * 128;
;             const f32x4 b0 = *(const f32x4*)(bias + c), b1 = *(const f32x4*)(bias + c + 4);
; #pragma unroll
;             for (int ai = 0; ai < 2; ++ai)
; #pragma unroll
;                 for (int m = 0; m < 4; ++m) {
;                     const f32x4 v0 = acc[ai][bj][m][0] + b0, v1 = acc[ai][bj][m][1] + b1;
;                     u32x4 w; w.x = cvt_pk(sigmoidf_(v0[0]), sigmoidf_(v0[1])); w.y = cvt_pk(sigmoidf_(v0[2]), sigmoidf_(v0[3]));
;                     w.z = cvt_pk(sigmoidf_(v1[0]), sigmoidf_(v1[1])); w.w = cvt_pk(sigmoidf_(v1[2]), sigmoidf_(v1[3]));
;                     *(u32x4*)(G + (size_t)(row0 + ai * 128 + m * 16) * (3 * DM) + c) = w;
;                 }
;         }
;     }
	v_pk_add_f32 v[98:99], v[98:99], s[100:101]
	v_rcp_f32_e32 v98, v98
	v_rcp_f32_e32 v99, v99
	v_exp_f32_e32 v91, v91
	v_add_f32_e32 v90, 1.0, v90
	v_rcp_f32_e32 v90, v90
	v_cvt_pk_bf16_f32 v103, v98, v99
	v_or_b32_e32 v98, 48, v154
	v_mad_i64_i32 v[98:99], s[6:7], v98, s13, v[132:133]
	v_lshl_add_u64 v[98:99], v[98:99], 0, v[134:135]
	global_store_dwordx4 v[98:99], v[100:103], off
	v_add_f32_e32 v91, 1.0, v91
	v_rcp_f32_e32 v91, v91
	v_pk_add_f32 v[100:101], v[92:93], v[108:109]
	v_pk_mul_f32 v[92:93], v[94:95], s[98:99]
	v_exp_f32_e32 v92, v92
	v_exp_f32_e32 v93, v93
	v_mul_f32_e32 v94, 0xbfb8aa3b, v97
	v_exp_f32_e32 v94, v94
	v_pk_add_f32 v[92:93], v[92:93], s[100:101]
	v_rcp_f32_e32 v92, v92
	v_rcp_f32_e32 v93, v93
	v_add_f32_e32 v94, 1.0, v94
	v_rcp_f32_e32 v94, v94
	v_add_u32_e32 v102, 0x80, v154
	v_cvt_pk_bf16_f32 v92, v92, v93
	v_mul_f32_e32 v93, 0xbfb8aa3b, v96
	v_exp_f32_e32 v93, v93
	v_pk_add_f32 v[88:89], v[88:89], v[112:113]
	v_pk_add_f32 v[82:83], v[82:83], v[106:107]
	v_pk_add_f32 v[78:79], v[78:79], v[110:111]
	v_add_f32_e32 v93, 1.0, v93
	v_rcp_f32_e32 v93, v93
	v_pk_mul_f32 v[82:83], v[82:83], s[98:99]
	v_exp_f32_e32 v82, v82
	v_cvt_pk_bf16_f32 v93, v93, v94
	v_cvt_pk_bf16_f32 v94, v90, v91
	v_pk_mul_f32 v[90:91], v[100:101], s[98:99]
	v_exp_f32_e32 v90, v90
	v_exp_f32_e32 v91, v91
	v_exp_f32_e32 v83, v83
	v_add_f32_e32 v82, 1.0, v82
	v_pk_add_f32 v[90:91], v[90:91], s[100:101]
	v_rcp_f32_e32 v90, v90
	v_rcp_f32_e32 v91, v91
	v_add_f32_e32 v83, 1.0, v83
	v_rcp_f32_e32 v82, v82
	v_rcp_f32_e32 v83, v83
	v_cvt_pk_bf16_f32 v95, v90, v91
	v_mad_i64_i32 v[90:91], s[6:7], v102, s13, v[132:133]
	v_lshl_add_u64 v[90:91], v[90:91], 0, v[134:135]
	global_store_dwordx4 v[90:91], v[92:95], off
	v_pk_add_f32 v[80:81], v[80:81], v[112:113]
	v_pk_add_f32 v[74:75], v[74:75], v[106:107]
	v_pk_add_f32 v[92:93], v[84:85], v[108:109]
	v_pk_mul_f32 v[84:85], v[86:87], s[98:99]
	v_exp_f32_e32 v84, v84
	v_exp_f32_e32 v85, v85
	v_mul_f32_e32 v86, 0xbfb8aa3b, v89
	v_exp_f32_e32 v86, v86
	v_pk_add_f32 v[84:85], v[84:85], s[100:101]
	v_rcp_f32_e32 v84, v84
	v_rcp_f32_e32 v85, v85
	v_add_f32_e32 v86, 1.0, v86
	v_rcp_f32_e32 v86, v86
	v_pk_mul_f32 v[74:75], v[74:75], s[98:99]
	v_cvt_pk_bf16_f32 v84, v84, v85
	v_mul_f32_e32 v85, 0xbfb8aa3b, v88
	v_exp_f32_e32 v85, v85
	v_exp_f32_e32 v74, v74
	v_exp_f32_e32 v75, v75
	v_add_f32_e32 v85, 1.0, v85
	v_rcp_f32_e32 v85, v85
	v_pk_add_f32 v[74:75], v[74:75], s[100:101]
	v_rcp_f32_e32 v74, v74
	v_cvt_pk_bf16_f32 v85, v85, v86
	v_cvt_pk_bf16_f32 v86, v82, v83
	v_pk_mul_f32 v[82:83], v[92:93], s[98:99]
	v_exp_f32_e32 v82, v82
	v_exp_f32_e32 v83, v83
	v_rcp_f32_e32 v75, v75
	v_pk_add_f32 v[70:71], v[70:71], v[110:111]
	v_pk_add_f32 v[82:83], v[82:83], s[100:101]
	v_rcp_f32_e32 v82, v82
	v_rcp_f32_e32 v83, v83
	v_pk_add_f32 v[72:73], v[72:73], v[112:113]
	v_exp_f32_e32 v130, v130
	v_exp_f32_e32 v131, v131
	v_cvt_pk_bf16_f32 v87, v82, v83
	v_add_u32_e32 v82, 0x90, v154
	v_mad_i64_i32 v[82:83], s[6:7], v82, s13, v[132:133]
	v_lshl_add_u64 v[82:83], v[82:83], 0, v[134:135]
	global_store_dwordx4 v[82:83], v[84:87], off
	v_pk_add_f32 v[130:131], v[130:131], s[100:101]
	s_nop 0
	v_pk_add_f32 v[84:85], v[76:77], v[108:109]
	v_pk_mul_f32 v[76:77], v[78:79], s[98:99]
	v_exp_f32_e32 v76, v76
	v_exp_f32_e32 v77, v77
	v_mul_f32_e32 v78, 0xbfb8aa3b, v81
	v_exp_f32_e32 v78, v78
	v_pk_add_f32 v[76:77], v[76:77], s[100:101]
	v_rcp_f32_e32 v76, v76
	v_rcp_f32_e32 v77, v77
	v_add_f32_e32 v78, 1.0, v78
	v_rcp_f32_e32 v78, v78
	v_rcp_f32_e32 v130, v130
	v_cvt_pk_bf16_f32 v76, v76, v77
	v_mul_f32_e32 v77, 0xbfb8aa3b, v80
	v_exp_f32_e32 v77, v77
	v_rcp_f32_e32 v131, v131
	v_add_f32_e32 v77, 1.0, v77
	v_rcp_f32_e32 v77, v77
	v_cvt_pk_bf16_f32 v159, v130, v131
	v_mad_i64_i32 v[130:131], s[6:7], v154, s13, v[132:133]
	v_cvt_pk_bf16_f32 v77, v77, v78
	v_cvt_pk_bf16_f32 v78, v74, v75
	v_pk_mul_f32 v[74:75], v[84:85], s[98:99]
	v_exp_f32_e32 v74, v74
	v_exp_f32_e32 v75, v75
	v_lshl_add_u64 v[130:131], v[130:131], 0, v[134:135]
	global_store_dwordx4 v[130:131], v[156:159], off
	v_pk_add_f32 v[74:75], v[74:75], s[100:101]
	v_rcp_f32_e32 v74, v74
	v_rcp_f32_e32 v75, v75
	s_nop 0
	v_cvt_pk_bf16_f32 v79, v74, v75
	v_add_u32_e32 v74, 0xa0, v154
	v_mad_i64_i32 v[74:75], s[6:7], v74, s13, v[132:133]
	v_lshl_add_u64 v[74:75], v[74:75], 0, v[134:135]
	global_store_dwordx4 v[74:75], v[76:79], off
	s_nop 1
	v_pk_add_f32 v[76:77], v[68:69], v[108:109]
	v_pk_add_f32 v[68:69], v[66:67], v[106:107]
	v_pk_mul_f32 v[66:67], v[70:71], s[98:99]
	v_exp_f32_e32 v66, v66
	v_exp_f32_e32 v67, v67
	v_mul_f32_e32 v70, 0xbfb8aa3b, v73
	v_pk_mul_f32 v[68:69], v[68:69], s[98:99]
	v_pk_add_f32 v[66:67], v[66:67], s[100:101]
	v_rcp_f32_e32 v66, v66
	v_rcp_f32_e32 v67, v67
	v_exp_f32_e32 v70, v70
	v_exp_f32_e32 v68, v68
	v_cvt_pk_bf16_f32 v66, v66, v67
	v_mul_f32_e32 v67, 0xbfb8aa3b, v72
	v_exp_f32_e32 v67, v67
	v_exp_f32_e32 v69, v69
	v_add_f32_e32 v70, 1.0, v70
	v_pk_add_f32 v[68:69], v[68:69], s[100:101]
	v_add_f32_e32 v67, 1.0, v67
	v_rcp_f32_e32 v67, v67
	v_rcp_f32_e32 v70, v70
	v_rcp_f32_e32 v68, v68
	v_rcp_f32_e32 v69, v69
	v_cvt_pk_bf16_f32 v67, v67, v70
	v_mul_f32_e32 v70, 0xbfb8aa3b, v77
	v_cvt_pk_bf16_f32 v68, v68, v69
	v_mul_f32_e32 v69, 0xbfb8aa3b, v76
	v_exp_f32_e32 v69, v69
	v_exp_f32_e32 v70, v70
	v_add_f32_e32 v69, 1.0, v69
	v_add_f32_e32 v70, 1.0, v70
	v_rcp_f32_e32 v69, v69
	v_rcp_f32_e32 v70, v70
	s_nop 0
	v_cvt_pk_bf16_f32 v69, v69, v70
	v_add_u32_e32 v70, 0xb0, v154
	v_mad_i64_i32 v[70:71], s[6:7], v70, s13, v[132:133]
	v_lshl_add_u64 v[76:77], v[70:71], 0, v[134:135]
	global_store_dwordx4 v[76:77], v[66:69], off
	global_load_dwordx4 v[66:69], v[148:149], off offset:528
	s_nop 0
	global_load_dwordx4 v[70:73], v[148:149], off offset:512
	s_mov_b64 s[6:7], -1
	s_waitcnt vmcnt(1)
; __device__ __forceinline__ unsigned cvt_pk(float lo, float hi) { f32x2_t v = {lo, hi}; bf16x2_t b = __builtin_convertvector(v, bf16x2_t); return __builtin_bit_cast(unsigned, b); }
; __device__ __forceinline__ float sigmoidf_(float x) { return __builtin_amdgcn_rcpf(1.0f + ex2(-x * LOG2E)); }
;     __device__ __forceinline__ void operator()(const f32x4 (&acc)[2][2][4][2], const Unit& u, int wr, int wc, int fr, int fq) const {
;         const int row0 = u.pm * 256 + wr * 64 + fr, col0 = u.pn * 256 + wc * 32 + 8 * fq;
; #pragma unroll
;         for (int bj = 0; bj < 2; ++bj) {
;             const int c = col0 + bj * 128;
;             const f32x4 b0 = *(const f32x4*)(bias + c), b1 = *(const f32x4*)(bias + c + 4);
; #pragma unroll
;             for (int ai = 0; ai < 2; ++ai)
; #pragma unroll
;                 for (int m = 0; m < 4; ++m) {
;                     const f32x4 v0 = acc[ai][bj][m][0] + b0, v1 = acc[ai][bj][m][1] + b1;
;                     u32x4 w; w.x = cvt_pk(sigmoidf_(v0[0]), sigmoidf_(v0[1])); w.y = cvt_pk(sigmoidf_(v0[2]), sigmoidf_(v0[3]));
;                     w.z = cvt_pk(sigmoidf_(v1[0]), sigmoidf_(v1[1])); w.w = cvt_pk(sigmoidf_(v1[2]), sigmoidf_(v1[3]));
;                     *(u32x4*)(G + (size_t)(row0 + ai * 128 + m * 16) * (3 * DM) + c) = w;
;                 }
;         }
;     }
	v_pk_add_f32 v[78:79], v[60:61], v[68:69]
	s_waitcnt vmcnt(0)
	v_pk_add_f32 v[62:63], v[62:63], v[70:71]
	v_pk_add_f32 v[60:61], v[58:59], v[66:67]
	v_pk_mul_f32 v[58:59], v[62:63], s[98:99]
	v_exp_f32_e32 v58, v58
	v_exp_f32_e32 v59, v59
	v_pk_add_f32 v[64:65], v[64:65], v[72:73]
	v_pk_mul_f32 v[60:61], v[60:61], s[98:99]
	v_pk_add_f32 v[58:59], v[58:59], s[100:101]
	v_rcp_f32_e32 v58, v58
	v_rcp_f32_e32 v59, v59
	v_mul_f32_e32 v62, 0xbfb8aa3b, v65
	v_exp_f32_e32 v62, v62
	v_cvt_pk_bf16_f32 v58, v58, v59
	v_mul_f32_e32 v59, 0xbfb8aa3b, v64
	v_exp_f32_e32 v59, v59
	v_exp_f32_e32 v60, v60
	v_exp_f32_e32 v61, v61
	v_add_f32_e32 v62, 1.0, v62
	v_add_f32_e32 v59, 1.0, v59
	v_pk_add_f32 v[60:61], v[60:61], s[100:101]
	v_rcp_f32_e32 v59, v59
	v_rcp_f32_e32 v62, v62
	v_rcp_f32_e32 v60, v60
	v_rcp_f32_e32 v61, v61
	v_pk_add_f32 v[54:55], v[54:55], v[70:71]
	v_cvt_pk_bf16_f32 v59, v59, v62
	v_mul_f32_e32 v62, 0xbfb8aa3b, v79
	v_cvt_pk_bf16_f32 v60, v60, v61
	v_mul_f32_e32 v61, 0xbfb8aa3b, v78
	v_exp_f32_e32 v61, v61
	v_exp_f32_e32 v62, v62
	v_pk_add_f32 v[56:57], v[56:57], v[72:73]
	v_pk_add_f32 v[46:47], v[46:47], v[70:71]
	v_add_f32_e32 v61, 1.0, v61
	v_add_f32_e32 v62, 1.0, v62
	v_rcp_f32_e32 v61, v61
	v_rcp_f32_e32 v62, v62
	v_pk_add_f32 v[48:49], v[48:49], v[72:73]
	v_pk_add_f32 v[38:39], v[38:39], v[70:71]
	v_pk_add_f32 v[40:41], v[40:41], v[72:73]
	v_cvt_pk_bf16_f32 v61, v61, v62
	global_store_dwordx4 v[130:131], v[58:61], off offset:256
	v_pk_add_f32 v[30:31], v[30:31], v[70:71]
	v_pk_add_f32 v[32:33], v[32:33], v[72:73]
	v_pk_add_f32 v[58:59], v[52:53], v[68:69]
	v_pk_add_f32 v[52:53], v[50:51], v[66:67]
	v_pk_mul_f32 v[50:51], v[54:55], s[98:99]
	v_exp_f32_e32 v50, v50
	v_exp_f32_e32 v51, v51
	v_mul_f32_e32 v54, 0xbfb8aa3b, v57
	v_pk_mul_f32 v[52:53], v[52:53], s[98:99]
	v_pk_add_f32 v[50:51], v[50:51], s[100:101]
	v_rcp_f32_e32 v50, v50
	v_rcp_f32_e32 v51, v51
	v_exp_f32_e32 v54, v54
	v_exp_f32_e32 v52, v52
	v_cvt_pk_bf16_f32 v50, v50, v51
	v_mul_f32_e32 v51, 0xbfb8aa3b, v56
	v_exp_f32_e32 v51, v51
	v_exp_f32_e32 v53, v53
	v_add_f32_e32 v54, 1.0, v54
	v_pk_add_f32 v[52:53], v[52:53], s[100:101]
	v_add_f32_e32 v51, 1.0, v51
	v_rcp_f32_e32 v51, v51
	v_rcp_f32_e32 v54, v54
	v_rcp_f32_e32 v52, v52
	v_rcp_f32_e32 v53, v53
	v_pk_add_f32 v[22:23], v[22:23], v[70:71]
	v_cvt_pk_bf16_f32 v51, v51, v54
	v_mul_f32_e32 v54, 0xbfb8aa3b, v59
	v_cvt_pk_bf16_f32 v52, v52, v53
	v_mul_f32_e32 v53, 0xbfb8aa3b, v58
	v_exp_f32_e32 v53, v53
	v_exp_f32_e32 v54, v54
	v_pk_add_f32 v[24:25], v[24:25], v[72:73]
	v_pk_add_f32 v[14:15], v[14:15], v[70:71]
	v_add_f32_e32 v53, 1.0, v53
	v_add_f32_e32 v54, 1.0, v54
	v_rcp_f32_e32 v53, v53
	v_rcp_f32_e32 v54, v54
	v_pk_add_f32 v[16:17], v[16:17], v[72:73]
	v_pk_add_f32 v[6:7], v[6:7], v[70:71]
	v_pk_add_f32 v[8:9], v[8:9], v[72:73]
	v_cvt_pk_bf16_f32 v53, v53, v54
	global_store_dwordx4 v[126:127], v[50:53], off offset:256
	s_nop 1
	v_pk_add_f32 v[50:51], v[44:45], v[68:69]
	v_pk_add_f32 v[44:45], v[42:43], v[66:67]
	v_pk_mul_f32 v[42:43], v[46:47], s[98:99]
	v_exp_f32_e32 v42, v42
	v_exp_f32_e32 v43, v43
	v_mul_f32_e32 v46, 0xbfb8aa3b, v49
	v_pk_mul_f32 v[44:45], v[44:45], s[98:99]
	v_pk_add_f32 v[42:43], v[42:43], s[100:101]
	v_rcp_f32_e32 v42, v42
	v_rcp_f32_e32 v43, v43
	v_exp_f32_e32 v46, v46
	v_exp_f32_e32 v44, v44
	v_cvt_pk_bf16_f32 v42, v42, v43
	v_mul_f32_e32 v43, 0xbfb8aa3b, v48
	v_exp_f32_e32 v43, v43
	v_exp_f32_e32 v45, v45
	v_add_f32_e32 v46, 1.0, v46
	v_pk_add_f32 v[44:45], v[44:45], s[100:101]
	v_add_f32_e32 v43, 1.0, v43
	v_rcp_f32_e32 v43, v43
	v_rcp_f32_e32 v46, v46
	v_rcp_f32_e32 v44, v44
	v_rcp_f32_e32 v45, v45
	v_cvt_pk_bf16_f32 v43, v43, v46
	v_mul_f32_e32 v46, 0xbfb8aa3b, v51
	v_cvt_pk_bf16_f32 v44, v44, v45
	v_mul_f32_e32 v45, 0xbfb8aa3b, v50
	v_exp_f32_e32 v45, v45
	v_exp_f32_e32 v46, v46
	v_add_f32_e32 v45, 1.0, v45
	v_add_f32_e32 v46, 1.0, v46
	v_rcp_f32_e32 v45, v45
	v_rcp_f32_e32 v46, v46
	s_nop 0
	v_cvt_pk_bf16_f32 v45, v45, v46
	global_store_dwordx4 v[114:115], v[42:45], off offset:256
	s_nop 1
	v_pk_add_f32 v[42:43], v[36:37], v[68:69]
	v_pk_add_f32 v[36:37], v[34:35], v[66:67]
	v_pk_mul_f32 v[34:35], v[38:39], s[98:99]
	v_exp_f32_e32 v34, v34
	v_exp_f32_e32 v35, v35
	v_mul_f32_e32 v38, 0xbfb8aa3b, v41
	v_pk_mul_f32 v[36:37], v[36:37], s[98:99]
	v_pk_add_f32 v[34:35], v[34:35], s[100:101]
	v_rcp_f32_e32 v34, v34
	v_rcp_f32_e32 v35, v35
	v_exp_f32_e32 v38, v38
	v_exp_f32_e32 v36, v36
	v_cvt_pk_bf16_f32 v34, v34, v35
	v_mul_f32_e32 v35, 0xbfb8aa3b, v40
	v_exp_f32_e32 v35, v35
	v_exp_f32_e32 v37, v37
	v_add_f32_e32 v38, 1.0, v38
	v_pk_add_f32 v[36:37], v[36:37], s[100:101]
	v_add_f32_e32 v35, 1.0, v35
	v_rcp_f32_e32 v35, v35
	v_rcp_f32_e32 v38, v38
	v_rcp_f32_e32 v36, v36
	v_rcp_f32_e32 v37, v37
	v_cvt_pk_bf16_f32 v35, v35, v38
	v_mul_f32_e32 v38, 0xbfb8aa3b, v43
; #define PG8_BAR __builtin_amdgcn_s_barrier()
; __device__ __forceinline__ unsigned cvt_pk(float lo, float hi) { f32x2_t v = {lo, hi}; bf16x2_t b = __builtin_convertvector(v, bf16x2_t); return __builtin_bit_cast(unsigned, b); }
; __device__ __forceinline__ float sigmoidf_(float x) { return __builtin_amdgcn_rcpf(1.0f + ex2(-x * LOG2E)); }
; template <class Epi, class Sched, bool ALIGN_EPI = false, bool SP2 = false>
; __device__ __forceinline__ void gemm_phase(PG8_LAS unsigned char* lds, const Gemm g, const Sched& S, const Epi& E) {
;     ...
;         if constexpr (ALIGN_EPI) { if (wr == 0) PG8_BAR; }
;         bool keep_acc = false;
;         if constexpr (!Epi::AFTER_DRAIN) { if constexpr (Epi::CARRY) keep_acc = E.carry(acc, cur, wr, wc, fr, fq); else E(acc, cur, wr, wc, fr, fq); S.done(cur); }
;         if (!has_next) break;
;         if (!keep_acc)
; #pragma unroll
;         for (int a = 0; a < 2; ++a)
; #pragma unroll
;             for (int b = 0; b < 2; ++b)
; #pragma unroll
;                 for (int m = 0; m < 4; ++m)
; #pragma unroll
;                     for (int n = 0; n < 2; ++n) acc[a][b][m][n] = (f32x4){0.f, 0.f, 0.f, 0.f};
;         cur = nxt; cA = nA; cB = nB; ++ui;
;         if constexpr (ALIGN_EPI) { if (wr == 1) PG8_BAR; }
;     __device__ __forceinline__ void operator()(const f32x4 (&acc)[2][2][4][2], const Unit& u, int wr, int wc, int fr, int fq) const {
;         const int row0 = u.pm * 256 + wr * 64 + fr, col0 = u.pn * 256 + wc * 32 + 8 * fq;
; #pragma unroll
;         for (int bj = 0; bj < 2; ++bj) {
;             const int c = col0 + bj * 128;
;             const f32x4 b0 = *(const f32x4*)(bias + c), b1 = *(const f32x4*)(bias + c + 4);
; #pragma unroll
;             for (int ai = 0; ai < 2; ++ai)
; #pragma unroll
;                 for (int m = 0; m < 4; ++m) {
;                     const f32x4 v0 = acc[ai][bj][m][0] + b0, v1 = acc[ai][bj][m][1] + b1;
;                     u32x4 w; w.x = cvt_pk(sigmoidf_(v0[0]), sigmoidf_(v0[1])); w.y = cvt_pk(sigmoidf_(v0[2]), sigmoidf_(v0[3]));
;                     w.z = cvt_pk(sigmoidf_(v1[0]), sigmoidf_(v1[1])); w.w = cvt_pk(sigmoidf_(v1[2]), sigmoidf_(v1[3]));
;                     *(u32x4*)(G + (size_t)(row0 + ai * 128 + m * 16) * (3 * DM) + c) = w;
;                 }
;         }
;     }
	v_cvt_pk_bf16_f32 v36, v36, v37
	v_mul_f32_e32 v37, 0xbfb8aa3b, v42
	v_exp_f32_e32 v37, v37
	v_exp_f32_e32 v38, v38
	v_add_f32_e32 v37, 1.0, v37
	v_add_f32_e32 v38, 1.0, v38
	v_rcp_f32_e32 v37, v37
	v_rcp_f32_e32 v38, v38
	s_nop 0
	v_cvt_pk_bf16_f32 v37, v37, v38
	global_store_dwordx4 v[98:99], v[34:37], off offset:256
	s_nop 1
	v_pk_add_f32 v[34:35], v[28:29], v[68:69]
	v_pk_add_f32 v[28:29], v[26:27], v[66:67]
	v_pk_mul_f32 v[26:27], v[30:31], s[98:99]
	v_exp_f32_e32 v26, v26
	v_exp_f32_e32 v27, v27
	v_mul_f32_e32 v30, 0xbfb8aa3b, v33
	v_pk_mul_f32 v[28:29], v[28:29], s[98:99]
	v_pk_add_f32 v[26:27], v[26:27], s[100:101]
	v_rcp_f32_e32 v26, v26
	v_rcp_f32_e32 v27, v27
	v_exp_f32_e32 v30, v30
	v_exp_f32_e32 v28, v28
	v_cvt_pk_bf16_f32 v26, v26, v27
	v_mul_f32_e32 v27, 0xbfb8aa3b, v32
	v_exp_f32_e32 v27, v27
	v_exp_f32_e32 v29, v29
	v_add_f32_e32 v30, 1.0, v30
	v_pk_add_f32 v[28:29], v[28:29], s[100:101]
	v_add_f32_e32 v27, 1.0, v27
	v_rcp_f32_e32 v27, v27
	v_rcp_f32_e32 v30, v30
	v_rcp_f32_e32 v28, v28
	v_rcp_f32_e32 v29, v29
	v_cvt_pk_bf16_f32 v27, v27, v30
	v_mul_f32_e32 v30, 0xbfb8aa3b, v35
	v_cvt_pk_bf16_f32 v28, v28, v29
	v_mul_f32_e32 v29, 0xbfb8aa3b, v34
	v_exp_f32_e32 v29, v29
	v_exp_f32_e32 v30, v30
	v_add_f32_e32 v29, 1.0, v29
	v_add_f32_e32 v30, 1.0, v30
	v_rcp_f32_e32 v29, v29
	v_rcp_f32_e32 v30, v30
	s_nop 0
	v_cvt_pk_bf16_f32 v29, v29, v30
	global_store_dwordx4 v[90:91], v[26:29], off offset:256
	s_nop 1
	v_pk_add_f32 v[26:27], v[20:21], v[68:69]
	v_pk_add_f32 v[20:21], v[18:19], v[66:67]
	v_pk_mul_f32 v[18:19], v[22:23], s[98:99]
	v_exp_f32_e32 v18, v18
	v_exp_f32_e32 v19, v19
	v_mul_f32_e32 v22, 0xbfb8aa3b, v25
	v_pk_mul_f32 v[20:21], v[20:21], s[98:99]
	v_pk_add_f32 v[18:19], v[18:19], s[100:101]
	v_rcp_f32_e32 v18, v18
	v_rcp_f32_e32 v19, v19
	v_exp_f32_e32 v22, v22
	v_exp_f32_e32 v20, v20
	v_cvt_pk_bf16_f32 v18, v18, v19
	v_mul_f32_e32 v19, 0xbfb8aa3b, v24
	v_exp_f32_e32 v19, v19
	v_exp_f32_e32 v21, v21
	v_add_f32_e32 v22, 1.0, v22
	v_pk_add_f32 v[20:21], v[20:21], s[100:101]
	v_add_f32_e32 v19, 1.0, v19
	v_rcp_f32_e32 v19, v19
	v_rcp_f32_e32 v22, v22
	v_rcp_f32_e32 v20, v20
	v_rcp_f32_e32 v21, v21
	v_cvt_pk_bf16_f32 v19, v19, v22
	v_mul_f32_e32 v22, 0xbfb8aa3b, v27
	v_cvt_pk_bf16_f32 v20, v20, v21
	v_mul_f32_e32 v21, 0xbfb8aa3b, v26
	v_exp_f32_e32 v21, v21
	v_exp_f32_e32 v22, v22
	v_add_f32_e32 v21, 1.0, v21
	v_add_f32_e32 v22, 1.0, v22
	v_rcp_f32_e32 v21, v21
	v_rcp_f32_e32 v22, v22
	s_nop 0
	v_cvt_pk_bf16_f32 v21, v21, v22
	global_store_dwordx4 v[82:83], v[18:21], off offset:256
	s_nop 1
	v_pk_add_f32 v[18:19], v[12:13], v[68:69]
	v_pk_add_f32 v[12:13], v[10:11], v[66:67]
	v_pk_mul_f32 v[10:11], v[14:15], s[98:99]
	v_exp_f32_e32 v10, v10
	v_exp_f32_e32 v11, v11
	v_mul_f32_e32 v14, 0xbfb8aa3b, v17
	v_pk_mul_f32 v[12:13], v[12:13], s[98:99]
	v_pk_add_f32 v[10:11], v[10:11], s[100:101]
	v_rcp_f32_e32 v10, v10
	v_rcp_f32_e32 v11, v11
	v_exp_f32_e32 v14, v14
	v_exp_f32_e32 v12, v12
	v_cvt_pk_bf16_f32 v10, v10, v11
	v_mul_f32_e32 v11, 0xbfb8aa3b, v16
	v_exp_f32_e32 v11, v11
	v_exp_f32_e32 v13, v13
	v_add_f32_e32 v14, 1.0, v14
	v_pk_add_f32 v[12:13], v[12:13], s[100:101]
	v_add_f32_e32 v11, 1.0, v11
	v_rcp_f32_e32 v11, v11
	v_rcp_f32_e32 v14, v14
	v_rcp_f32_e32 v12, v12
	v_rcp_f32_e32 v13, v13
	v_cvt_pk_bf16_f32 v11, v11, v14
	v_mul_f32_e32 v14, 0xbfb8aa3b, v19
	v_cvt_pk_bf16_f32 v12, v12, v13
	v_mul_f32_e32 v13, 0xbfb8aa3b, v18
	v_exp_f32_e32 v13, v13
	v_exp_f32_e32 v14, v14
	v_add_f32_e32 v13, 1.0, v13
	v_add_f32_e32 v14, 1.0, v14
	v_rcp_f32_e32 v13, v13
	v_rcp_f32_e32 v14, v14
	s_nop 0
	v_cvt_pk_bf16_f32 v13, v13, v14
	global_store_dwordx4 v[74:75], v[10:13], off offset:256
	s_nop 1
	v_pk_add_f32 v[10:11], v[4:5], v[68:69]
	v_pk_add_f32 v[4:5], v[2:3], v[66:67]
	v_pk_mul_f32 v[2:3], v[6:7], s[98:99]
	v_exp_f32_e32 v2, v2
	v_exp_f32_e32 v3, v3
	v_mul_f32_e32 v6, 0xbfb8aa3b, v9
	v_pk_mul_f32 v[4:5], v[4:5], s[98:99]
	v_pk_add_f32 v[2:3], v[2:3], s[100:101]
	v_rcp_f32_e32 v2, v2
	v_rcp_f32_e32 v3, v3
	v_exp_f32_e32 v6, v6
	v_exp_f32_e32 v4, v4
	v_cvt_pk_bf16_f32 v2, v2, v3
	v_mul_f32_e32 v3, 0xbfb8aa3b, v8
	v_exp_f32_e32 v3, v3
	v_exp_f32_e32 v5, v5
	v_add_f32_e32 v6, 1.0, v6
	v_pk_add_f32 v[4:5], v[4:5], s[100:101]
	v_add_f32_e32 v3, 1.0, v3
	v_rcp_f32_e32 v3, v3
	v_rcp_f32_e32 v6, v6
	v_rcp_f32_e32 v4, v4
	v_rcp_f32_e32 v5, v5
	v_cvt_pk_bf16_f32 v3, v3, v6
	v_mul_f32_e32 v6, 0xbfb8aa3b, v11
	v_cvt_pk_bf16_f32 v4, v4, v5
	v_mul_f32_e32 v5, 0xbfb8aa3b, v10
	v_exp_f32_e32 v5, v5
	v_exp_f32_e32 v6, v6
	v_add_f32_e32 v5, 1.0, v5
	v_add_f32_e32 v6, 1.0, v6
	v_rcp_f32_e32 v5, v5
	v_rcp_f32_e32 v6, v6
	s_nop 0
	v_cvt_pk_bf16_f32 v5, v5, v6
	global_store_dwordx4 v[76:77], v[2:5], off offset:256
	s_cbranch_vccnz .LBB0_125
	s_andn2_b64 vcc, exec, s[0:1]
	s_cbranch_vccnz .LBB0_124
	s_barrier
	s_branch .LBB0_124

; __device__ __forceinline__ unsigned cvt_pk(float lo, float hi) { f32x2_t v = {lo, hi}; bf16x2_t b = __builtin_convertvector(v, bf16x2_t); return __builtin_bit_cast(unsigned, b); }
; __device__ __forceinline__ float ex2(float x) { return __builtin_amdgcn_exp2f(x); }
; __device__ __forceinline__ float sigmoidf_(float x) { return __builtin_amdgcn_rcpf(1.0f + ex2(-x * LOG2E)); }
;     __device__ __forceinline__ void operator()(const f32x4 (&acc)[2][2][4][2], const Unit& u, int wr, int wc, int fr, int fq) const {
;         const int row0 = u.pm * 256 + wr * 64 + fr, col0 = u.pn * 128 + wc * 32 + 8 * fq;
; #pragma unroll
;         for (int ai = 0; ai < 2; ++ai)
; #pragma unroll
;             for (int m = 0; m < 4; ++m) {
;                 bf16_t* rowp = H + (size_t)(row0 + ai * 128 + m * 16) * DFF + col0;
;                 float h[8];
; #pragma unroll
;                 for (int n = 0; n < 2; ++n)
; #pragma unroll
;                     for (int e = 0; e < 4; ++e) { const float g = acc[ai][0][m][n][e], up = acc[ai][1][m][n][e]; h[n * 4 + e] = g * sigmoidf_(g) * up; }
;                 u32x4 w; w.x = cvt_pk(h[0], h[1]); w.y = cvt_pk(h[2], h[3]); w.z = cvt_pk(h[4], h[5]); w.w = cvt_pk(h[6], h[7]);
;                 *(u32x4*)rowp = w;
;             }
;     }
.LBB0_876:
	s_mov_b32 s98, 0xbfb8aa3b
	s_mov_b32 s99, 0xbfb8aa3b
	s_mov_b32 s100, 1.0
	s_mov_b32 s101, 1.0
	v_pk_mul_f32 v[140:141], v[126:127], s[98:99]
	v_exp_f32_e32 v140, v140
	v_exp_f32_e32 v141, v141
	v_mul_f32_e32 v147, 0xbfb8aa3b, v128
	v_add_f32_e32 v140, 1.0, v140
	v_rcp_f32_e32 v150, v140
	v_add_f32_e32 v140, 1.0, v141
	v_rcp_f32_e32 v151, v140
	v_exp_f32_e32 v147, v147
	v_readlane_b32 s6, v252, 37
	v_lshl_or_b32 v148, s13, 7, v145
	v_pk_mul_f32 v[126:127], v[126:127], v[150:151]
	v_mul_f32_e32 v150, 0xbfb8aa3b, v129
	v_exp_f32_e32 v150, v150
	v_pk_mul_f32 v[118:119], v[126:127], v[118:119]
	v_add_f32_e32 v126, 1.0, v147
	v_mul_f32_e32 v147, 0xbfb8aa3b, v122
	v_add_f32_e32 v127, 1.0, v150
	v_rcp_f32_e32 v126, v126
	v_rcp_f32_e32 v127, v127
	v_exp_f32_e32 v147, v147
	v_mul_f32_e32 v150, 0xbfb8aa3b, v123
	v_exp_f32_e32 v150, v150
	v_pk_mul_f32 v[126:127], v[128:129], v[126:127]
	v_add_f32_e32 v128, 1.0, v147
	v_mul_f32_e32 v147, 0xbfb8aa3b, v124
	v_add_f32_e32 v129, 1.0, v150
	v_exp_f32_e32 v147, v147
	v_mul_f32_e32 v150, 0xbfb8aa3b, v125
	v_exp_f32_e32 v151, v150
	v_rcp_f32_e32 v128, v128
	v_add_f32_e32 v147, 1.0, v147
	v_rcp_f32_e32 v129, v129
	v_rcp_f32_e32 v150, v147
	v_add_f32_e32 v147, 1.0, v151
	v_rcp_f32_e32 v151, v147
	v_pk_mul_f32 v[122:123], v[122:123], v[128:129]
	v_pk_mul_f32 v[120:121], v[126:127], v[120:121]
	v_pk_mul_f32 v[122:123], v[122:123], v[114:115]
	v_pk_mul_f32 v[114:115], v[124:125], v[150:151]
	v_readlane_b32 s7, v252, 38
	v_pk_mul_f32 v[124:125], v[114:115], v[116:117]
	v_cvt_pk_bf16_f32 v117, v120, v121
	v_pk_mul_f32 v[120:121], v[110:111], s[98:99]
	v_exp_f32_e32 v120, v120
	v_exp_f32_e32 v121, v121
	v_lshl_add_u32 v146, s46, 8, v142
	v_ashrrev_i32_e32 v149, 31, v148
	v_mov_b64_e32 v[140:141], s[6:7]
	s_movk_i32 s13, 0x1600
	v_mad_i64_i32 v[152:153], s[6:7], v146, s13, v[140:141]
	v_lshlrev_b64 v[114:115], 1, v[148:149]
	v_lshl_add_u64 v[126:127], v[152:153], 0, v[114:115]
	v_cvt_pk_bf16_f32 v116, v118, v119
	v_cvt_pk_bf16_f32 v118, v122, v123
	v_cvt_pk_bf16_f32 v119, v124, v125
	global_store_dwordx4 v[126:127], v[116:119], off
	s_andn2_b64 vcc, exec, s[38:39]
	s_nop 0
	v_add_f32_e32 v116, 1.0, v120
	v_add_f32_e32 v117, 1.0, v121
	v_rcp_f32_e32 v116, v116
	v_rcp_f32_e32 v117, v117
	v_or_b32_e32 v118, 16, v146
	v_mad_i64_i32 v[118:119], s[6:7], v118, s13, v[140:141]
	v_pk_mul_f32 v[110:111], v[110:111], v[116:117]
	v_pk_mul_f32 v[116:117], v[112:113], s[98:99]
	v_exp_f32_e32 v116, v116
	v_exp_f32_e32 v117, v117
	v_pk_mul_f32 v[102:103], v[110:111], v[102:103]
	v_add_f32_e32 v110, 1.0, v116
	v_add_f32_e32 v111, 1.0, v117
	v_pk_mul_f32 v[116:117], v[106:107], s[98:99]
	v_rcp_f32_e32 v110, v110
	v_rcp_f32_e32 v111, v111
	v_exp_f32_e32 v116, v116
	v_exp_f32_e32 v117, v117
	v_pk_mul_f32 v[110:111], v[112:113], v[110:111]
	v_add_f32_e32 v112, 1.0, v116
	v_add_f32_e32 v113, 1.0, v117
	v_pk_mul_f32 v[116:117], v[108:109], s[98:99]
	v_exp_f32_e32 v116, v116
	v_exp_f32_e32 v117, v117
	v_rcp_f32_e32 v112, v112
	v_rcp_f32_e32 v113, v113
	v_pk_add_f32 v[116:117], v[116:117], s[100:101]
	v_rcp_f32_e32 v116, v116
	v_rcp_f32_e32 v117, v117
	v_pk_mul_f32 v[106:107], v[106:107], v[112:113]
	v_pk_mul_f32 v[104:105], v[110:111], v[104:105]
	v_pk_mul_f32 v[106:107], v[106:107], v[98:99]
	v_pk_mul_f32 v[98:99], v[108:109], v[116:117]
	v_lshl_add_u64 v[110:111], v[118:119], 0, v[114:115]
	v_pk_mul_f32 v[108:109], v[98:99], v[100:101]
	v_cvt_pk_bf16_f32 v98, v102, v103
	v_pk_mul_f32 v[102:103], v[94:95], s[98:99]
	v_exp_f32_e32 v102, v102
	v_exp_f32_e32 v103, v103
	v_cvt_pk_bf16_f32 v99, v104, v105
	v_cvt_pk_bf16_f32 v100, v106, v107
	v_cvt_pk_bf16_f32 v101, v108, v109
	global_store_dwordx4 v[110:111], v[98:101], off
	s_nop 1
	v_add_f32_e32 v98, 1.0, v102
	v_add_f32_e32 v99, 1.0, v103
	v_rcp_f32_e32 v98, v98
	v_rcp_f32_e32 v99, v99
	v_or_b32_e32 v100, 32, v146
	v_mad_i64_i32 v[100:101], s[6:7], v100, s13, v[140:141]
	v_pk_mul_f32 v[94:95], v[94:95], v[98:99]
	v_pk_mul_f32 v[98:99], v[96:97], s[98:99]
	v_exp_f32_e32 v98, v98
	v_exp_f32_e32 v99, v99
	v_pk_mul_f32 v[86:87], v[94:95], v[86:87]
	v_add_f32_e32 v94, 1.0, v98
	v_add_f32_e32 v95, 1.0, v99
	v_pk_mul_f32 v[98:99], v[90:91], s[98:99]
	v_rcp_f32_e32 v94, v94
	v_rcp_f32_e32 v95, v95
	v_exp_f32_e32 v98, v98
	v_exp_f32_e32 v99, v99
	v_pk_mul_f32 v[94:95], v[96:97], v[94:95]
	v_add_f32_e32 v96, 1.0, v98
	v_add_f32_e32 v97, 1.0, v99
	v_pk_mul_f32 v[98:99], v[92:93], s[98:99]
	v_exp_f32_e32 v98, v98
	v_exp_f32_e32 v99, v99
	v_rcp_f32_e32 v96, v96
	v_rcp_f32_e32 v97, v97
	v_pk_add_f32 v[98:99], v[98:99], s[100:101]
	v_rcp_f32_e32 v98, v98
	v_rcp_f32_e32 v99, v99
	v_pk_mul_f32 v[90:91], v[90:91], v[96:97]
	v_pk_mul_f32 v[88:89], v[94:95], v[88:89]
	v_pk_mul_f32 v[90:91], v[90:91], v[82:83]
	v_pk_mul_f32 v[82:83], v[92:93], v[98:99]
	v_lshl_add_u64 v[94:95], v[100:101], 0, v[114:115]
	v_pk_mul_f32 v[92:93], v[82:83], v[84:85]
	v_cvt_pk_bf16_f32 v82, v86, v87
	v_pk_mul_f32 v[86:87], v[78:79], s[98:99]
	v_exp_f32_e32 v86, v86
	v_exp_f32_e32 v87, v87
	v_cvt_pk_bf16_f32 v83, v88, v89
	v_cvt_pk_bf16_f32 v84, v90, v91
	v_cvt_pk_bf16_f32 v85, v92, v93
	global_store_dwordx4 v[94:95], v[82:85], off
	s_nop 1
	v_add_f32_e32 v82, 1.0, v86
	v_add_f32_e32 v83, 1.0, v87
	v_rcp_f32_e32 v82, v82
	v_rcp_f32_e32 v83, v83
	v_or_b32_e32 v84, 48, v146
	v_mad_i64_i32 v[84:85], s[6:7], v84, s13, v[140:141]
	v_pk_mul_f32 v[78:79], v[78:79], v[82:83]
	v_pk_mul_f32 v[82:83], v[80:81], s[98:99]
	v_exp_f32_e32 v82, v82
	v_exp_f32_e32 v83, v83
	v_pk_mul_f32 v[70:71], v[78:79], v[70:71]
	v_add_f32_e32 v78, 1.0, v82
	v_add_f32_e32 v79, 1.0, v83
	v_pk_mul_f32 v[82:83], v[74:75], s[98:99]
	v_rcp_f32_e32 v78, v78
; #define PG8_BAR __builtin_amdgcn_s_barrier()
; __device__ __forceinline__ unsigned cvt_pk(float lo, float hi) { f32x2_t v = {lo, hi}; bf16x2_t b = __builtin_convertvector(v, bf16x2_t); return __builtin_bit_cast(unsigned, b); }
; __device__ __forceinline__ float sigmoidf_(float x) { return __builtin_amdgcn_rcpf(1.0f + ex2(-x * LOG2E)); }
; template <class Epi, class Sched, bool ALIGN_EPI = false, bool SP2 = false>
; __device__ __forceinline__ void gemm_phase(PG8_LAS unsigned char* lds, const Gemm g, const Sched& S, const Epi& E) {
;     ...
;         if constexpr (ALIGN_EPI) { if (wr == 0) PG8_BAR; }
;         bool keep_acc = false;
;         if constexpr (!Epi::AFTER_DRAIN) { if constexpr (Epi::CARRY) keep_acc = E.carry(acc, cur, wr, wc, fr, fq); else E(acc, cur, wr, wc, fr, fq); S.done(cur); }
;         if (!has_next) break;
;         if (!keep_acc)
; #pragma unroll
;         for (int a = 0; a < 2; ++a)
; #pragma unroll
;             for (int b = 0; b < 2; ++b)
; #pragma unroll
;                 for (int m = 0; m < 4; ++m)
; #pragma unroll
;                     for (int n = 0; n < 2; ++n) acc[a][b][m][n] = (f32x4){0.f, 0.f, 0.f, 0.f};
;         cur = nxt; cA = nA; cB = nB; ++ui;
;         if constexpr (ALIGN_EPI) { if (wr == 1) PG8_BAR; }
;     __device__ __forceinline__ void operator()(const f32x4 (&acc)[2][2][4][2], const Unit& u, int wr, int wc, int fr, int fq) const {
;         const int row0 = u.pm * 256 + wr * 64 + fr, col0 = u.pn * 128 + wc * 32 + 8 * fq;
; #pragma unroll
;         for (int ai = 0; ai < 2; ++ai)
; #pragma unroll
;             for (int m = 0; m < 4; ++m) {
;                 bf16_t* rowp = H + (size_t)(row0 + ai * 128 + m * 16) * DFF + col0;
;                 float h[8];
; #pragma unroll
;                 for (int n = 0; n < 2; ++n)
; #pragma unroll
;                     for (int e = 0; e < 4; ++e) { const float g = acc[ai][0][m][n][e], up = acc[ai][1][m][n][e]; h[n * 4 + e] = g * sigmoidf_(g) * up; }
;                 u32x4 w; w.x = cvt_pk(h[0], h[1]); w.y = cvt_pk(h[2], h[3]); w.z = cvt_pk(h[4], h[5]); w.w = cvt_pk(h[6], h[7]);
;                 *(u32x4*)rowp = w;
;             }
;     }
	v_rcp_f32_e32 v79, v79
	v_exp_f32_e32 v82, v82
	v_exp_f32_e32 v83, v83
	v_pk_mul_f32 v[78:79], v[80:81], v[78:79]
	v_add_f32_e32 v80, 1.0, v82
	v_add_f32_e32 v81, 1.0, v83
	v_pk_mul_f32 v[82:83], v[76:77], s[98:99]
	v_exp_f32_e32 v82, v82
	v_exp_f32_e32 v83, v83
	v_rcp_f32_e32 v80, v80
	v_rcp_f32_e32 v81, v81
	v_pk_add_f32 v[82:83], v[82:83], s[100:101]
	v_rcp_f32_e32 v82, v82
	v_rcp_f32_e32 v83, v83
	v_pk_mul_f32 v[74:75], v[74:75], v[80:81]
	v_pk_mul_f32 v[72:73], v[78:79], v[72:73]
	v_pk_mul_f32 v[74:75], v[74:75], v[66:67]
	v_pk_mul_f32 v[66:67], v[76:77], v[82:83]
	v_lshl_add_u64 v[78:79], v[84:85], 0, v[114:115]
	v_pk_mul_f32 v[76:77], v[66:67], v[68:69]
	v_cvt_pk_bf16_f32 v66, v70, v71
	v_pk_mul_f32 v[70:71], v[62:63], s[98:99]
	v_exp_f32_e32 v70, v70
	v_exp_f32_e32 v71, v71
	v_cvt_pk_bf16_f32 v67, v72, v73
	v_cvt_pk_bf16_f32 v68, v74, v75
	v_cvt_pk_bf16_f32 v69, v76, v77
	global_store_dwordx4 v[78:79], v[66:69], off
	s_nop 1
	v_add_f32_e32 v66, 1.0, v70
	v_add_f32_e32 v67, 1.0, v71
	v_rcp_f32_e32 v66, v66
	v_rcp_f32_e32 v67, v67
	v_add_u32_e32 v68, 0x80, v146
	v_mad_i64_i32 v[68:69], s[6:7], v68, s13, v[140:141]
	v_pk_mul_f32 v[62:63], v[62:63], v[66:67]
	v_pk_mul_f32 v[66:67], v[64:65], s[98:99]
	v_exp_f32_e32 v66, v66
	v_exp_f32_e32 v67, v67
	v_pk_mul_f32 v[54:55], v[62:63], v[54:55]
	v_add_f32_e32 v62, 1.0, v66
	v_add_f32_e32 v63, 1.0, v67
	v_pk_mul_f32 v[66:67], v[58:59], s[98:99]
	v_rcp_f32_e32 v62, v62
	v_rcp_f32_e32 v63, v63
	v_exp_f32_e32 v66, v66
	v_exp_f32_e32 v67, v67
	v_pk_mul_f32 v[62:63], v[64:65], v[62:63]
	v_add_f32_e32 v64, 1.0, v66
	v_add_f32_e32 v65, 1.0, v67
	v_pk_mul_f32 v[66:67], v[60:61], s[98:99]
	v_exp_f32_e32 v66, v66
	v_exp_f32_e32 v67, v67
	v_rcp_f32_e32 v64, v64
	v_rcp_f32_e32 v65, v65
	v_pk_add_f32 v[66:67], v[66:67], s[100:101]
	v_rcp_f32_e32 v66, v66
	v_rcp_f32_e32 v67, v67
	v_pk_mul_f32 v[58:59], v[58:59], v[64:65]
	v_pk_mul_f32 v[56:57], v[62:63], v[56:57]
	v_pk_mul_f32 v[58:59], v[58:59], v[50:51]
	v_pk_mul_f32 v[50:51], v[60:61], v[66:67]
	v_lshl_add_u64 v[62:63], v[68:69], 0, v[114:115]
	v_pk_mul_f32 v[60:61], v[50:51], v[52:53]
	v_cvt_pk_bf16_f32 v50, v54, v55
	v_pk_mul_f32 v[54:55], v[46:47], s[98:99]
	v_exp_f32_e32 v54, v54
	v_exp_f32_e32 v55, v55
	v_cvt_pk_bf16_f32 v51, v56, v57
	v_cvt_pk_bf16_f32 v52, v58, v59
	v_cvt_pk_bf16_f32 v53, v60, v61
	global_store_dwordx4 v[62:63], v[50:53], off
	s_nop 1
	v_add_f32_e32 v50, 1.0, v54
	v_add_f32_e32 v51, 1.0, v55
	v_rcp_f32_e32 v50, v50
	v_rcp_f32_e32 v51, v51
	v_add_u32_e32 v52, 0x90, v146
	v_mad_i64_i32 v[52:53], s[6:7], v52, s13, v[140:141]
	v_pk_mul_f32 v[46:47], v[46:47], v[50:51]
	v_pk_mul_f32 v[50:51], v[48:49], s[98:99]
	v_exp_f32_e32 v50, v50
	v_exp_f32_e32 v51, v51
	v_pk_mul_f32 v[38:39], v[46:47], v[38:39]
	v_add_f32_e32 v46, 1.0, v50
	v_add_f32_e32 v47, 1.0, v51
	v_pk_mul_f32 v[50:51], v[42:43], s[98:99]
	v_rcp_f32_e32 v46, v46
	v_rcp_f32_e32 v47, v47
	v_exp_f32_e32 v50, v50
	v_exp_f32_e32 v51, v51
	v_pk_mul_f32 v[46:47], v[48:49], v[46:47]
	v_add_f32_e32 v48, 1.0, v50
	v_add_f32_e32 v49, 1.0, v51
	v_pk_mul_f32 v[50:51], v[44:45], s[98:99]
	v_exp_f32_e32 v50, v50
	v_exp_f32_e32 v51, v51
	v_rcp_f32_e32 v48, v48
	v_rcp_f32_e32 v49, v49
	v_pk_add_f32 v[50:51], v[50:51], s[100:101]
	v_rcp_f32_e32 v50, v50
	v_rcp_f32_e32 v51, v51
	v_pk_mul_f32 v[42:43], v[42:43], v[48:49]
	v_pk_mul_f32 v[40:41], v[46:47], v[40:41]
	v_pk_mul_f32 v[42:43], v[42:43], v[34:35]
	v_pk_mul_f32 v[34:35], v[44:45], v[50:51]
	v_lshl_add_u64 v[46:47], v[52:53], 0, v[114:115]
	v_pk_mul_f32 v[44:45], v[34:35], v[36:37]
	v_cvt_pk_bf16_f32 v34, v38, v39
	v_pk_mul_f32 v[38:39], v[30:31], s[98:99]
	v_exp_f32_e32 v38, v38
	v_exp_f32_e32 v39, v39
	v_cvt_pk_bf16_f32 v35, v40, v41
	v_cvt_pk_bf16_f32 v36, v42, v43
	v_cvt_pk_bf16_f32 v37, v44, v45
	global_store_dwordx4 v[46:47], v[34:37], off
	s_nop 1
	v_add_f32_e32 v34, 1.0, v38
	v_add_f32_e32 v35, 1.0, v39
	v_rcp_f32_e32 v34, v34
	v_rcp_f32_e32 v35, v35
	v_add_u32_e32 v36, 0xa0, v146
	v_mad_i64_i32 v[36:37], s[6:7], v36, s13, v[140:141]
	v_pk_mul_f32 v[30:31], v[30:31], v[34:35]
	v_pk_mul_f32 v[34:35], v[32:33], s[98:99]
	v_exp_f32_e32 v34, v34
	v_exp_f32_e32 v35, v35
	v_pk_mul_f32 v[22:23], v[30:31], v[22:23]
	v_add_f32_e32 v30, 1.0, v34
	v_add_f32_e32 v31, 1.0, v35
	v_pk_mul_f32 v[34:35], v[26:27], s[98:99]
	v_rcp_f32_e32 v30, v30
	v_rcp_f32_e32 v31, v31
	v_exp_f32_e32 v34, v34
	v_exp_f32_e32 v35, v35
	v_pk_mul_f32 v[30:31], v[32:33], v[30:31]
	v_add_f32_e32 v32, 1.0, v34
	v_add_f32_e32 v33, 1.0, v35
	v_pk_mul_f32 v[34:35], v[28:29], s[98:99]
	v_exp_f32_e32 v34, v34
	v_exp_f32_e32 v35, v35
	v_rcp_f32_e32 v32, v32
	v_rcp_f32_e32 v33, v33
	v_pk_add_f32 v[34:35], v[34:35], s[100:101]
	v_rcp_f32_e32 v34, v34
	v_rcp_f32_e32 v35, v35
	v_pk_mul_f32 v[26:27], v[26:27], v[32:33]
	v_pk_mul_f32 v[24:25], v[30:31], v[24:25]
	v_pk_mul_f32 v[26:27], v[26:27], v[18:19]
	v_pk_mul_f32 v[18:19], v[28:29], v[34:35]
	v_lshl_add_u64 v[30:31], v[36:37], 0, v[114:115]
	v_pk_mul_f32 v[28:29], v[18:19], v[20:21]
	v_cvt_pk_bf16_f32 v18, v22, v23
	v_pk_mul_f32 v[22:23], v[14:15], s[98:99]
	v_exp_f32_e32 v22, v22
	v_exp_f32_e32 v23, v23
	v_cvt_pk_bf16_f32 v19, v24, v25
	v_cvt_pk_bf16_f32 v20, v26, v27
	v_cvt_pk_bf16_f32 v21, v28, v29
	global_store_dwordx4 v[30:31], v[18:21], off
	s_nop 1
	v_add_f32_e32 v18, 1.0, v22
	v_add_f32_e32 v19, 1.0, v23
	v_rcp_f32_e32 v18, v18
	v_rcp_f32_e32 v19, v19
	v_add_u32_e32 v20, 0xb0, v146
	v_mad_i64_i32 v[20:21], s[6:7], v20, s13, v[140:141]
	v_pk_mul_f32 v[14:15], v[14:15], v[18:19]
	v_pk_mul_f32 v[18:19], v[16:17], s[98:99]
	v_exp_f32_e32 v18, v18
	v_exp_f32_e32 v19, v19
	v_pk_mul_f32 v[6:7], v[14:15], v[6:7]
	s_mov_b64 s[6:7], -1
	v_add_f32_e32 v14, 1.0, v18
	v_add_f32_e32 v15, 1.0, v19
	v_pk_mul_f32 v[18:19], v[10:11], s[98:99]
	v_rcp_f32_e32 v14, v14
	v_rcp_f32_e32 v15, v15
	v_exp_f32_e32 v18, v18
	v_exp_f32_e32 v19, v19
	v_pk_mul_f32 v[14:15], v[16:17], v[14:15]
	v_add_f32_e32 v16, 1.0, v18
	v_add_f32_e32 v17, 1.0, v19
	v_pk_mul_f32 v[18:19], v[12:13], s[98:99]
	v_exp_f32_e32 v18, v18
	v_exp_f32_e32 v19, v19
	v_rcp_f32_e32 v16, v16
	v_rcp_f32_e32 v17, v17
	v_pk_add_f32 v[18:19], v[18:19], s[100:101]
	v_rcp_f32_e32 v18, v18
	v_rcp_f32_e32 v19, v19
	v_pk_mul_f32 v[10:11], v[10:11], v[16:17]
	v_pk_mul_f32 v[8:9], v[14:15], v[8:9]
	v_pk_mul_f32 v[10:11], v[10:11], v[2:3]
	v_pk_mul_f32 v[2:3], v[12:13], v[18:19]
	v_lshl_add_u64 v[14:15], v[20:21], 0, v[114:115]
	v_pk_mul_f32 v[12:13], v[2:3], v[4:5]
	v_cvt_pk_bf16_f32 v2, v6, v7
	v_cvt_pk_bf16_f32 v3, v8, v9
	v_cvt_pk_bf16_f32 v4, v10, v11
	v_cvt_pk_bf16_f32 v5, v12, v13
	global_store_dwordx4 v[14:15], v[2:5], off
	s_cbranch_vccnz .LBB0_869
	s_andn2_b64 vcc, exec, s[0:1]
	s_cbranch_vccnz .LBB0_868
	s_barrier
	s_branch .LBB0_868
